# GEMM prologues (first tile of each GEMM phase): the second K-tile's 6 LDS-DMA loads are issued before the first wait+barrier (wait recounted 2 -> 8), so both K-tiles' load latencies overlap
# speedup vs baseline: 1.0015x; 1.0015x over previous
.LBB0_260:
	s_mul_i32 s26, s4, 0x7800
	s_lshl_b64 s[14:15], s[26:27], 2
	v_readlane_b32 s16, v254, 18
	v_lshrrev_b32_e32 v18, 1, v8
	s_add_u32 s44, s16, s14
	v_readlane_b32 s14, v254, 19
	v_and_b32_e32 v18, 24, v18
	v_readlane_b32 s56, v255, 8
	s_addc_u32 s45, s14, s15
	v_and_b32_e32 v9, 15, v8
	v_lshlrev_b32_e32 v19, 1, v18
	v_lshlrev_b32_e32 v8, 2, v8
	s_lshl_b32 s1, s1, 5
	v_readlane_b32 s57, v255, 9
	v_lshl_or_b32 v193, s10, 6, v9
	v_lshl_or_b32 v9, v9, 6, v19
	s_lshl_b32 s10, s10, 13
	v_and_b32_e32 v8, 32, v8
	s_and_b32 s1, s1, 0x60
	v_lshl_add_u64 v[10:11], s[56:57], 0, v[0:1]
	v_mov_b32_e32 v155, v1
	v_readlane_b32 s22, v255, 4
	v_bitop3_b32 v19, v9, s10, v8 bitop3:0xde
	s_lshl_b32 s10, s1, 7
	v_lshl_add_u64 v[12:13], s[56:57], 0, v[154:155]
	v_mov_b32_e32 v159, v1
	v_readlane_b32 s23, v255, 5
	v_bitop3_b32 v202, v9, s10, v8 bitop3:0xde
	s_add_i32 m0, s80, 0x18000
	v_lshl_add_u64 v[8:9], v[10:11], 0, s[28:29]
	v_lshl_add_u64 v[14:15], s[22:23], 0, v[158:159]
	v_mov_b32_e32 v157, v1
	global_load_lds_dwordx4 v[8:9], off
	v_lshl_add_u64 v[8:9], v[12:13], 0, s[28:29]
	s_add_i32 m0, s80, 0x1a000
	s_add_i32 s26, s80, 0x8000
	v_lshl_add_u64 v[16:17], s[22:23], 0, v[156:157]
	global_load_lds_dwordx4 v[8:9], off
	v_lshl_add_u64 v[8:9], v[14:15], 0, s[28:29]
	s_mov_b32 m0, s26
	s_add_i32 s20, s80, 0xa000
	v_readlane_b32 s14, v255, 10
	global_load_lds_dwordx4 v[8:9], off
	v_lshl_add_u64 v[8:9], v[16:17], 0, s[28:29]
	s_mov_b32 m0, s20
	v_readlane_b32 s15, v255, 11
	global_load_lds_dwordx4 v[8:9], off
	s_add_i32 m0, s80, 0x1c000
	v_lshl_add_u64 v[8:9], s[14:15], 0, v[0:1]
	global_load_lds_dwordx4 v[8:9], off
	v_lshl_add_u64 v[8:9], s[14:15], 0, v[154:155]
	s_add_i32 m0, s80, 0x1e000
	s_cmpk_lt_u32 s0, 0x100
	global_load_lds_dwordx4 v[8:9], off
	s_waitcnt vmcnt(8)
	s_barrier
	v_lshlrev_b32_e32 v8, 14, v6
	v_and_b32_e32 v8, 0xffff8000, v8
	v_lshl_add_u32 v5, v5, 11, v8
	v_and_b32_e32 v6, 1, v6
	v_lshl_or_b32 v5, v6, 6, v5
	v_lshl_add_u32 v160, v7, 1, v5
	v_lshlrev_b32_e32 v5, 14, v2
	v_and_b32_e32 v5, 0xffff8000, v5
	s_waitcnt vmcnt(6)
	v_lshl_add_u32 v3, v3, 11, v5
	v_and_b32_e32 v2, 1, v2
	v_or_b32_e32 v205, s1, v18
	v_lshl_or_b32 v2, v2, 6, v3
	v_readlane_b32 s0, v255, 0
	s_cselect_b64 s[46:47], -1, 0
	v_add_u32_e32 v203, 0x80, v193
	v_add_u32_e32 v204, 0xfffff700, v193
	v_mov_b32_e32 v161, v1
	v_lshl_add_u32 v162, v4, 1, v2
	v_mov_b32_e32 v163, v1
	s_mov_b32 s58, 0
	v_add_u32_e32 v206, 0, v19
	v_readlane_b32 s21, v254, 63
	s_mov_b32 s10, s0
	s_barrier
	v_readlane_b32 s1, v255, 1
	s_branch .LBB0_263

.LBB0_782:
	s_mul_i32 s17, s4, 0x1e000
	s_mul_hi_u32 s16, s4, 0x1e000
	s_add_u32 s17, s76, s17
	s_addc_u32 s16, s77, s16
	v_bfe_u32 v20, v13, 4, 2
	s_add_u32 s80, s17, 0x2202000
	v_and_b32_e32 v19, 15, v13
	v_lshlrev_b32_e32 v21, 4, v20
	v_lshlrev_b32_e32 v13, 2, v13
	v_readlane_b32 s48, v255, 15
	s_addc_u32 s81, s16, 0
	v_lshl_or_b32 v193, s10, 6, v19
	v_lshl_or_b32 v19, v19, 6, v21
	s_lshl_b32 s10, s10, 13
	v_and_b32_e32 v13, 32, v13
	s_lshl_b32 s1, s1, 5
	v_mov_b32_e32 v205, v1
	v_readlane_b32 s49, v255, 16
	v_bitop3_b32 v21, v19, s10, v13 bitop3:0xde
	s_and_b32 s10, s1, 0x60
	s_add_i32 m0, s25, 0x18000
	v_lshl_add_u64 v[2:3], v[2:3], 0, s[28:29]
	v_lshl_add_u64 v[14:15], s[48:49], 0, v[204:205]
	v_mov_b32_e32 v201, v1
	s_lshl_b32 s1, s10, 7
	global_load_lds_dwordx4 v[2:3], off
	v_lshl_add_u64 v[2:3], v[4:5], 0, s[28:29]
	s_add_i32 m0, s25, 0x1a000
	s_add_i32 s59, s25, 0x8000
	s_add_i32 s21, s25, 0xa000
	v_lshl_add_u64 v[16:17], s[48:49], 0, v[200:201]
	global_load_lds_dwordx4 v[2:3], off
	v_lshl_add_u64 v[2:3], v[14:15], 0, s[28:29]
	s_mov_b32 m0, s59
	s_add_u32 s16, s50, 0x40080
	global_load_lds_dwordx4 v[2:3], off
	v_lshl_add_u64 v[2:3], v[16:17], 0, s[28:29]
	s_mov_b32 m0, s21
	s_addc_u32 s17, s51, 0
	global_load_lds_dwordx4 v[2:3], off
	s_add_i32 m0, s25, 0x1c000
	v_lshl_add_u64 v[2:3], s[16:17], 0, v[202:203]
	global_load_lds_dwordx4 v[2:3], off
	v_lshl_add_u64 v[2:3], s[16:17], 0, v[198:199]
	s_add_i32 m0, s25, 0x1e000
	s_movk_i32 s16, 0x900
	global_load_lds_dwordx4 v[2:3], off
	s_waitcnt vmcnt(8)
	s_barrier
	v_lshrrev_b32_e32 v2, 1, v10
	v_mul_lo_u32 v0, v0, s16
	s_mov_b32 s17, 0x9000
	v_bitop3_b32 v240, v19, s1, v13 bitop3:0xde
	s_cmpk_lt_u32 s0, 0x100
	v_mad_u64_u32 v[2:3], s[0:1], v2, s17, v[0:1]
	v_or_b32_e32 v0, v2, v11
	v_add_lshl_u32 v0, v0, v12, 1
	s_mov_b64 s[22:23], 0x90080
	v_lshl_add_u64 v[206:207], v[0:1], 0, s[22:23]
	v_lshrrev_b32_e32 v2, 1, v6
	v_mul_lo_u32 v0, v7, s16
	v_mad_u64_u32 v[2:3], s[0:1], v2, s17, v[0:1]
	s_waitcnt vmcnt(6)
	v_or_b32_e32 v0, v2, v8
	v_mov_b32_e32 v4, v1
	v_mov_b32_e32 v5, v1
	v_lshlrev_b32_e32 v18, 3, v20
	v_add_lshl_u32 v0, v0, v9, 1
	v_mov_b32_e32 v2, v1
	v_mov_b32_e32 v3, v1
	v_mov_b64_e32 v[8:9], v[4:5]
	s_cselect_b64 s[44:45], -1, 0
	s_mov_b32 s82, 0
	v_cmp_eq_u32_e64 s[38:39], 0, v20
	v_or_b32_e32 v241, s10, v18
	v_lshl_add_u64 v[208:209], v[0:1], 0, s[22:23]
	s_lshl_b32 s26, s10, 1
	v_lshlrev_b32_e32 v0, 1, v18
	v_add_u32_e32 v242, 0, v21
	v_readlane_b32 s1, v254, 62
	v_readlane_b32 s0, v255, 14
	v_mov_b64_e32 v[6:7], v[2:3]
	s_movk_i32 s62, 0x61
	s_barrier
	s_branch .LBB0_785
